# v71 + all neutral work removals combined: widened attention stores, rotated fast-loop edge, guard-banded bias LUT, remaining P0 transpose loops de-serialised
# speedup vs baseline: 1.0068x; 1.0068x over previous
.LBB0_44:
	s_lshl_b32 s43, s28, 1
	s_lshl_b32 s52, s29, 1
	v_or_b32_e32 v130, s43, v21
	v_or_b32_e32 v132, s52, v70
	v_lshlrev_b32_sdwa v134, v108, v132 dst_sel:DWORD dst_unused:UNUSED_PAD src0_sel:DWORD src1_sel:WORD_0
	v_lshlrev_b32_sdwa v135, v108, v130 dst_sel:DWORD dst_unused:UNUSED_PAD src0_sel:DWORD src1_sel:WORD_0
	v_mov_b32_e32 v131, v3
	v_mov_b32_e32 v133, v3
	global_load_dword v162, v134, s[10:11]
	global_load_dword v163, v135, s[10:11]
	v_lshlrev_b64 v[132:133], 12, v[132:133]
	v_lshlrev_b64 v[130:131], 12, v[130:131]
	v_lshl_add_u64 v[132:133], v[68:69], 0, v[132:133]
	v_lshl_add_u64 v[130:131], v[68:69], 0, v[130:131]
	global_load_dword v164, v[132:133], off
	global_load_dword v165, v[130:131], off
	s_add_i32 s70, s43, 4
	s_add_i32 s71, s52, 4
	v_or_b32_e32 v130, s70, v21
	v_or_b32_e32 v132, s71, v70
	v_lshlrev_b32_sdwa v134, v108, v132 dst_sel:DWORD dst_unused:UNUSED_PAD src0_sel:DWORD src1_sel:WORD_0
	v_lshlrev_b32_sdwa v135, v108, v130 dst_sel:DWORD dst_unused:UNUSED_PAD src0_sel:DWORD src1_sel:WORD_0
	v_mov_b32_e32 v131, v3
	v_mov_b32_e32 v133, v3
	global_load_dword v166, v134, s[10:11]
	global_load_dword v167, v135, s[10:11]
	v_lshlrev_b64 v[132:133], 12, v[132:133]
	v_lshlrev_b64 v[130:131], 12, v[130:131]
	v_lshl_add_u64 v[132:133], v[68:69], 0, v[132:133]
	v_lshl_add_u64 v[130:131], v[68:69], 0, v[130:131]
	global_load_dword v168, v[132:133], off
	global_load_dword v169, v[130:131], off
	s_add_i32 s70, s43, 8
	s_add_i32 s71, s52, 8
	v_or_b32_e32 v130, s70, v21
	v_or_b32_e32 v132, s71, v70
	v_lshlrev_b32_sdwa v134, v108, v132 dst_sel:DWORD dst_unused:UNUSED_PAD src0_sel:DWORD src1_sel:WORD_0
	v_lshlrev_b32_sdwa v135, v108, v130 dst_sel:DWORD dst_unused:UNUSED_PAD src0_sel:DWORD src1_sel:WORD_0
	v_mov_b32_e32 v131, v3
	v_mov_b32_e32 v133, v3
	global_load_dword v170, v134, s[10:11]
	global_load_dword v171, v135, s[10:11]
	v_lshlrev_b64 v[132:133], 12, v[132:133]
	v_lshlrev_b64 v[130:131], 12, v[130:131]
	v_lshl_add_u64 v[132:133], v[68:69], 0, v[132:133]
	v_lshl_add_u64 v[130:131], v[68:69], 0, v[130:131]
	global_load_dword v172, v[132:133], off
	global_load_dword v173, v[130:131], off
	s_add_i32 s70, s43, 12
	s_add_i32 s71, s52, 12
	v_or_b32_e32 v130, s70, v21
	v_or_b32_e32 v132, s71, v70
	v_lshlrev_b32_sdwa v134, v108, v132 dst_sel:DWORD dst_unused:UNUSED_PAD src0_sel:DWORD src1_sel:WORD_0
	v_lshlrev_b32_sdwa v135, v108, v130 dst_sel:DWORD dst_unused:UNUSED_PAD src0_sel:DWORD src1_sel:WORD_0
	v_mov_b32_e32 v131, v3
	v_mov_b32_e32 v133, v3
	global_load_dword v174, v134, s[10:11]
	global_load_dword v175, v135, s[10:11]
	v_lshlrev_b64 v[132:133], 12, v[132:133]
	v_lshlrev_b64 v[130:131], 12, v[130:131]
	v_lshl_add_u64 v[132:133], v[68:69], 0, v[132:133]
	v_lshl_add_u64 v[130:131], v[68:69], 0, v[130:131]
	global_load_dword v176, v[132:133], off
	global_load_dword v177, v[130:131], off
	s_add_i32 s70, s43, 16
	s_add_i32 s71, s52, 16
	v_or_b32_e32 v130, s70, v21
	v_or_b32_e32 v132, s71, v70
	v_lshlrev_b32_sdwa v134, v108, v132 dst_sel:DWORD dst_unused:UNUSED_PAD src0_sel:DWORD src1_sel:WORD_0
	v_lshlrev_b32_sdwa v135, v108, v130 dst_sel:DWORD dst_unused:UNUSED_PAD src0_sel:DWORD src1_sel:WORD_0
	v_mov_b32_e32 v131, v3
	v_mov_b32_e32 v133, v3
	global_load_dword v178, v134, s[10:11]
	global_load_dword v179, v135, s[10:11]
	v_lshlrev_b64 v[132:133], 12, v[132:133]
	v_lshlrev_b64 v[130:131], 12, v[130:131]
	v_lshl_add_u64 v[132:133], v[68:69], 0, v[132:133]
	v_lshl_add_u64 v[130:131], v[68:69], 0, v[130:131]
	global_load_dword v180, v[132:133], off
	global_load_dword v181, v[130:131], off
	s_add_i32 s70, s43, 20
	s_add_i32 s71, s52, 20
	v_or_b32_e32 v130, s70, v21
	v_or_b32_e32 v132, s71, v70
	v_lshlrev_b32_sdwa v134, v108, v132 dst_sel:DWORD dst_unused:UNUSED_PAD src0_sel:DWORD src1_sel:WORD_0
	v_lshlrev_b32_sdwa v135, v108, v130 dst_sel:DWORD dst_unused:UNUSED_PAD src0_sel:DWORD src1_sel:WORD_0
	v_mov_b32_e32 v131, v3
	v_mov_b32_e32 v133, v3
	global_load_dword v182, v134, s[10:11]
	global_load_dword v183, v135, s[10:11]
	v_lshlrev_b64 v[132:133], 12, v[132:133]
	v_lshlrev_b64 v[130:131], 12, v[130:131]
	v_lshl_add_u64 v[132:133], v[68:69], 0, v[132:133]
	v_lshl_add_u64 v[130:131], v[68:69], 0, v[130:131]
	global_load_dword v184, v[132:133], off
	global_load_dword v185, v[130:131], off
	s_add_i32 s70, s43, 24
	s_add_i32 s71, s52, 24
	v_or_b32_e32 v130, s70, v21
	v_or_b32_e32 v132, s71, v70
	v_lshlrev_b32_sdwa v134, v108, v132 dst_sel:DWORD dst_unused:UNUSED_PAD src0_sel:DWORD src1_sel:WORD_0
	v_lshlrev_b32_sdwa v135, v108, v130 dst_sel:DWORD dst_unused:UNUSED_PAD src0_sel:DWORD src1_sel:WORD_0
	v_mov_b32_e32 v131, v3
	v_mov_b32_e32 v133, v3
	global_load_dword v186, v134, s[10:11]
	global_load_dword v187, v135, s[10:11]
	v_lshlrev_b64 v[132:133], 12, v[132:133]
	v_lshlrev_b64 v[130:131], 12, v[130:131]
	v_lshl_add_u64 v[132:133], v[68:69], 0, v[132:133]
	v_lshl_add_u64 v[130:131], v[68:69], 0, v[130:131]
	global_load_dword v188, v[132:133], off
	global_load_dword v189, v[130:131], off
	s_add_i32 s70, s43, 28
	s_add_i32 s71, s52, 28
	v_or_b32_e32 v130, s70, v21
	v_or_b32_e32 v132, s71, v70
	v_lshlrev_b32_sdwa v134, v108, v132 dst_sel:DWORD dst_unused:UNUSED_PAD src0_sel:DWORD src1_sel:WORD_0
	v_lshlrev_b32_sdwa v135, v108, v130 dst_sel:DWORD dst_unused:UNUSED_PAD src0_sel:DWORD src1_sel:WORD_0
	v_mov_b32_e32 v131, v3
	v_mov_b32_e32 v133, v3
	global_load_dword v190, v134, s[10:11]
	global_load_dword v191, v135, s[10:11]
	v_lshlrev_b64 v[132:133], 12, v[132:133]
	v_lshlrev_b64 v[130:131], 12, v[130:131]
	v_lshl_add_u64 v[132:133], v[68:69], 0, v[132:133]
	v_lshl_add_u64 v[130:131], v[68:69], 0, v[130:131]
	global_load_dword v192, v[132:133], off
	global_load_dword v193, v[130:131], off
	s_add_i32 s29, s29, 16
	s_add_i32 s28, s28, 16
	s_add_i32 s33, s33, -16
	s_waitcnt vmcnt(0)
	v_or_b32_e32 v61, s43, v1
	v_or_b32_e32 v71, s52, v20
	v_pk_mul_f32 v[162:163], v[162:163], s[16:17] op_sel_hi:[1,0]
	v_pk_mul_f32 v[72:73], v[162:163], v[164:165]
	v_mad_u64_u32 v[74:75], vcc, v71, s56, v[22:23]
	v_mad_u64_u32 v[76:77], vcc, v61, s56, v[22:23]
	ds_write_b32 v74, v72
	ds_write_b32 v76, v73
	s_add_i32 s70, s43, 4
	s_add_i32 s71, s52, 4
	v_or_b32_e32 v61, s70, v1
	v_or_b32_e32 v71, s71, v20
	v_pk_mul_f32 v[166:167], v[166:167], s[16:17] op_sel_hi:[1,0]
	v_pk_mul_f32 v[72:73], v[166:167], v[168:169]
	v_mad_u64_u32 v[74:75], vcc, v71, s56, v[22:23]
	v_mad_u64_u32 v[76:77], vcc, v61, s56, v[22:23]
	ds_write_b32 v74, v72
	ds_write_b32 v76, v73
	s_add_i32 s70, s43, 8
	s_add_i32 s71, s52, 8
	v_or_b32_e32 v61, s70, v1
	v_or_b32_e32 v71, s71, v20
	v_pk_mul_f32 v[170:171], v[170:171], s[16:17] op_sel_hi:[1,0]
	v_pk_mul_f32 v[72:73], v[170:171], v[172:173]
	v_mad_u64_u32 v[74:75], vcc, v71, s56, v[22:23]
	v_mad_u64_u32 v[76:77], vcc, v61, s56, v[22:23]
	ds_write_b32 v74, v72
	ds_write_b32 v76, v73
	s_add_i32 s70, s43, 12
	s_add_i32 s71, s52, 12
	v_or_b32_e32 v61, s70, v1
	v_or_b32_e32 v71, s71, v20
	v_pk_mul_f32 v[174:175], v[174:175], s[16:17] op_sel_hi:[1,0]
	v_pk_mul_f32 v[72:73], v[174:175], v[176:177]
	v_mad_u64_u32 v[74:75], vcc, v71, s56, v[22:23]
	v_mad_u64_u32 v[76:77], vcc, v61, s56, v[22:23]
	ds_write_b32 v74, v72
	ds_write_b32 v76, v73
	s_add_i32 s70, s43, 16
	s_add_i32 s71, s52, 16
	v_or_b32_e32 v61, s70, v1
	v_or_b32_e32 v71, s71, v20
	v_pk_mul_f32 v[178:179], v[178:179], s[16:17] op_sel_hi:[1,0]
	v_pk_mul_f32 v[72:73], v[178:179], v[180:181]
	v_mad_u64_u32 v[74:75], vcc, v71, s56, v[22:23]
	v_mad_u64_u32 v[76:77], vcc, v61, s56, v[22:23]
	ds_write_b32 v74, v72
	ds_write_b32 v76, v73
	s_add_i32 s70, s43, 20
	s_add_i32 s71, s52, 20
	v_or_b32_e32 v61, s70, v1
	v_or_b32_e32 v71, s71, v20
	v_pk_mul_f32 v[182:183], v[182:183], s[16:17] op_sel_hi:[1,0]
	v_pk_mul_f32 v[72:73], v[182:183], v[184:185]
	v_mad_u64_u32 v[74:75], vcc, v71, s56, v[22:23]
	v_mad_u64_u32 v[76:77], vcc, v61, s56, v[22:23]
	ds_write_b32 v74, v72
	ds_write_b32 v76, v73
	s_add_i32 s70, s43, 24
	s_add_i32 s71, s52, 24
	v_or_b32_e32 v61, s70, v1
	v_or_b32_e32 v71, s71, v20
	v_pk_mul_f32 v[186:187], v[186:187], s[16:17] op_sel_hi:[1,0]
	v_pk_mul_f32 v[72:73], v[186:187], v[188:189]
	v_mad_u64_u32 v[74:75], vcc, v71, s56, v[22:23]
	v_mad_u64_u32 v[76:77], vcc, v61, s56, v[22:23]
	ds_write_b32 v74, v72
	ds_write_b32 v76, v73
	s_add_i32 s70, s43, 28
	s_add_i32 s71, s52, 28
	v_or_b32_e32 v61, s70, v1
	v_or_b32_e32 v71, s71, v20
	v_pk_mul_f32 v[190:191], v[190:191], s[16:17] op_sel_hi:[1,0]
	v_pk_mul_f32 v[72:73], v[190:191], v[192:193]
	v_mad_u64_u32 v[74:75], vcc, v71, s56, v[22:23]
	v_mad_u64_u32 v[76:77], vcc, v61, s56, v[22:23]
	ds_write_b32 v74, v72
	ds_write_b32 v76, v73
	s_add_i32 s43, s43, 28
	s_add_i32 s52, s52, 28
	s_cmp_lg_u32 s33, 0
	s_cbranch_scc1 .LBB0_44
	s_waitcnt lgkmcnt(0)
	ds_read2_b32 v[72:73], v99 offset1:8
	ds_read2_b32 v[76:77], v99 offset0:33 offset1:41
	ds_read2_b32 v[78:79], v99 offset0:66 offset1:74
	ds_read2_b32 v[80:81], v99 offset0:99 offset1:107
	ds_read2_b32 v[82:83], v99 offset0:132 offset1:140
	s_waitcnt lgkmcnt(4)
	v_bfe_u32 v2, v72, 16, 1
	v_add3_u32 v2, v72, v2, s62
	s_waitcnt lgkmcnt(3)
	v_bfe_u32 v21, v76, 16, 1
	v_lshrrev_b32_e32 v2, 16, v2
	v_add3_u32 v21, v76, v21, s62
	ds_read2_b32 v[84:85], v99 offset0:165 offset1:173
	v_and_or_b32 v68, v21, s63, v2
	s_waitcnt lgkmcnt(3)
	v_bfe_u32 v2, v78, 16, 1
	v_add3_u32 v2, v78, v2, s62
	s_waitcnt lgkmcnt(2)
	v_bfe_u32 v21, v80, 16, 1
	ds_read2_b32 v[86:87], v99 offset0:198 offset1:206
	v_lshrrev_b32_e32 v2, 16, v2
	v_add3_u32 v21, v80, v21, s62
	ds_read2_b32 v[88:89], v99 offset0:231 offset1:239
	v_and_or_b32 v69, v21, s63, v2
	s_waitcnt lgkmcnt(3)
	v_bfe_u32 v2, v82, 16, 1
	v_add3_u32 v2, v82, v2, s62
	s_waitcnt lgkmcnt(2)
	v_bfe_u32 v21, v84, 16, 1
	v_lshrrev_b32_e32 v2, 16, v2
	v_add3_u32 v21, v84, v21, s62
	v_and_or_b32 v70, v21, s63, v2
	s_waitcnt lgkmcnt(1)
	v_bfe_u32 v2, v86, 16, 1
	v_add3_u32 v2, v86, v2, s62
	s_waitcnt lgkmcnt(0)
	v_bfe_u32 v21, v88, 16, 1
	s_bitset1_b32 s3, 11
	v_lshrrev_b32_e32 v2, 16, v2
	v_add3_u32 v21, v88, v21, s62
	s_lshl_b32 s52, s2, 1
	v_and_or_b32 v71, v21, s63, v2
	v_or_b32_e32 v2, s3, v23
	v_lshl_add_u64 v[74:75], v[6:7], 0, s[52:53]
	v_lshlrev_b32_e32 v2, 11, v2
	v_lshl_add_u64 v[90:91], v[74:75], 0, v[2:3]
	v_bfe_u32 v2, v73, 16, 1
	v_add3_u32 v2, v73, v2, s62
	v_bfe_u32 v21, v77, 16, 1
	v_lshrrev_b32_e32 v2, 16, v2
	v_add3_u32 v21, v77, v21, s62
	global_store_dwordx4 v[90:91], v[68:71], off
	ds_read2_b32 v[72:73], v99 offset0:16 offset1:24
	s_nop 0
	v_and_or_b32 v68, v21, s63, v2
	v_bfe_u32 v2, v79, 16, 1
	v_add3_u32 v2, v79, v2, s62
	v_bfe_u32 v21, v81, 16, 1
	v_lshrrev_b32_e32 v2, 16, v2
	v_add3_u32 v21, v81, v21, s62
	v_and_or_b32 v69, v21, s63, v2
	v_bfe_u32 v2, v83, 16, 1
	v_add3_u32 v2, v83, v2, s62
	v_bfe_u32 v21, v85, 16, 1
	v_lshrrev_b32_e32 v2, 16, v2
	v_add3_u32 v21, v85, v21, s62
	v_and_or_b32 v70, v21, s63, v2
	v_bfe_u32 v2, v87, 16, 1
	v_add3_u32 v2, v87, v2, s62
	v_bfe_u32 v21, v89, 16, 1
	v_lshrrev_b32_e32 v2, 16, v2
	v_add3_u32 v21, v89, v21, s62
	v_and_or_b32 v71, v21, s63, v2
	v_or_b32_e32 v2, s3, v51
	v_lshlrev_b32_e32 v2, 11, v2
	v_lshl_add_u64 v[76:77], v[74:75], 0, v[2:3]
	global_store_dwordx4 v[76:77], v[68:71], off
	ds_read2_b32 v[76:77], v99 offset0:49 offset1:57
	ds_read2_b32 v[78:79], v99 offset0:82 offset1:90
	ds_read2_b32 v[80:81], v99 offset0:115 offset1:123
	s_waitcnt lgkmcnt(3)
	v_bfe_u32 v2, v72, 16, 1
	v_add3_u32 v2, v72, v2, s62
	s_waitcnt lgkmcnt(2)
	v_bfe_u32 v21, v76, 16, 1
	ds_read2_b32 v[82:83], v99 offset0:148 offset1:156
	v_lshrrev_b32_e32 v2, 16, v2
	v_add3_u32 v21, v76, v21, s62
	ds_read2_b32 v[84:85], v99 offset0:181 offset1:189
	v_and_or_b32 v68, v21, s63, v2
	s_waitcnt lgkmcnt(3)
	v_bfe_u32 v2, v78, 16, 1
	v_add3_u32 v2, v78, v2, s62
	s_waitcnt lgkmcnt(2)
	v_bfe_u32 v21, v80, 16, 1
	ds_read2_b32 v[86:87], v99 offset0:214 offset1:222
	v_lshrrev_b32_e32 v2, 16, v2
	v_add3_u32 v21, v80, v21, s62
	ds_read2_b32 v[88:89], v99 offset0:247 offset1:255
	v_and_or_b32 v69, v21, s63, v2
	s_waitcnt lgkmcnt(3)
	v_bfe_u32 v2, v82, 16, 1
	v_add3_u32 v2, v82, v2, s62
	s_waitcnt lgkmcnt(2)
	v_bfe_u32 v21, v84, 16, 1
	v_lshrrev_b32_e32 v2, 16, v2
	v_add3_u32 v21, v84, v21, s62
	v_and_or_b32 v70, v21, s63, v2
	s_waitcnt lgkmcnt(1)
	v_bfe_u32 v2, v86, 16, 1
	v_add3_u32 v2, v86, v2, s62
	s_waitcnt lgkmcnt(0)
	v_bfe_u32 v21, v88, 16, 1
	v_lshrrev_b32_e32 v2, 16, v2
	v_add3_u32 v21, v88, v21, s62
	v_and_or_b32 v71, v21, s63, v2
	v_or_b32_e32 v2, s3, v53
	v_lshlrev_b32_e32 v2, 11, v2
	v_lshl_add_u64 v[90:91], v[74:75], 0, v[2:3]
	v_bfe_u32 v2, v73, 16, 1
	v_add3_u32 v2, v73, v2, s62
	v_bfe_u32 v21, v77, 16, 1
	v_lshrrev_b32_e32 v2, 16, v2
	v_add3_u32 v21, v77, v21, s62
	global_store_dwordx4 v[90:91], v[68:71], off
	s_nop 1
	v_and_or_b32 v68, v21, s63, v2
	v_bfe_u32 v2, v79, 16, 1
	v_add3_u32 v2, v79, v2, s62
	v_bfe_u32 v21, v81, 16, 1
	v_lshrrev_b32_e32 v2, 16, v2
	v_add3_u32 v21, v81, v21, s62
	v_and_or_b32 v69, v21, s63, v2
	v_bfe_u32 v2, v83, 16, 1
	v_add3_u32 v2, v83, v2, s62
	v_bfe_u32 v21, v85, 16, 1
	v_lshrrev_b32_e32 v2, 16, v2
	v_add3_u32 v21, v85, v21, s62
	v_and_or_b32 v70, v21, s63, v2
	v_bfe_u32 v2, v87, 16, 1
	v_add3_u32 v2, v87, v2, s62
	v_bfe_u32 v21, v89, 16, 1
	v_lshrrev_b32_e32 v2, 16, v2
	v_add3_u32 v21, v89, v21, s62
	v_and_or_b32 v71, v21, s63, v2
	v_or_b32_e32 v2, s3, v98
	v_lshlrev_b32_e32 v2, 11, v2
	v_lshl_add_u64 v[72:73], v[74:75], 0, v[2:3]
	global_store_dwordx4 v[72:73], v[68:71], off
	s_waitcnt lgkmcnt(0)

.LBB0_80:
	s_lshl_b32 s43, s28, 1
	s_lshl_b32 s52, s29, 1
	v_or_b32_e32 v130, s43, v21
	v_or_b32_e32 v132, s52, v70
	v_lshlrev_b32_sdwa v134, v108, v132 dst_sel:DWORD dst_unused:UNUSED_PAD src0_sel:DWORD src1_sel:WORD_0
	v_lshlrev_b32_sdwa v135, v108, v130 dst_sel:DWORD dst_unused:UNUSED_PAD src0_sel:DWORD src1_sel:WORD_0
	v_mov_b32_e32 v131, v3
	v_mov_b32_e32 v133, v3
	global_load_dword v162, v134, s[14:15]
	global_load_dword v163, v135, s[14:15]
	v_lshlrev_b64 v[132:133], 14, v[132:133]
	v_lshlrev_b64 v[130:131], 14, v[130:131]
	v_lshl_add_u64 v[132:133], v[68:69], 0, v[132:133]
	v_lshl_add_u64 v[130:131], v[68:69], 0, v[130:131]
	global_load_dword v164, v[132:133], off
	global_load_dword v165, v[130:131], off
	s_add_i32 s70, s43, 4
	s_add_i32 s71, s52, 4
	v_or_b32_e32 v130, s70, v21
	v_or_b32_e32 v132, s71, v70
	v_lshlrev_b32_sdwa v134, v108, v132 dst_sel:DWORD dst_unused:UNUSED_PAD src0_sel:DWORD src1_sel:WORD_0
	v_lshlrev_b32_sdwa v135, v108, v130 dst_sel:DWORD dst_unused:UNUSED_PAD src0_sel:DWORD src1_sel:WORD_0
	v_mov_b32_e32 v131, v3
	v_mov_b32_e32 v133, v3
	global_load_dword v166, v134, s[14:15]
	global_load_dword v167, v135, s[14:15]
	v_lshlrev_b64 v[132:133], 14, v[132:133]
	v_lshlrev_b64 v[130:131], 14, v[130:131]
	v_lshl_add_u64 v[132:133], v[68:69], 0, v[132:133]
	v_lshl_add_u64 v[130:131], v[68:69], 0, v[130:131]
	global_load_dword v168, v[132:133], off
	global_load_dword v169, v[130:131], off
	s_add_i32 s70, s43, 8
	s_add_i32 s71, s52, 8
	v_or_b32_e32 v130, s70, v21
	v_or_b32_e32 v132, s71, v70
	v_lshlrev_b32_sdwa v134, v108, v132 dst_sel:DWORD dst_unused:UNUSED_PAD src0_sel:DWORD src1_sel:WORD_0
	v_lshlrev_b32_sdwa v135, v108, v130 dst_sel:DWORD dst_unused:UNUSED_PAD src0_sel:DWORD src1_sel:WORD_0
	v_mov_b32_e32 v131, v3
	v_mov_b32_e32 v133, v3
	global_load_dword v170, v134, s[14:15]
	global_load_dword v171, v135, s[14:15]
	v_lshlrev_b64 v[132:133], 14, v[132:133]
	v_lshlrev_b64 v[130:131], 14, v[130:131]
	v_lshl_add_u64 v[132:133], v[68:69], 0, v[132:133]
	v_lshl_add_u64 v[130:131], v[68:69], 0, v[130:131]
	global_load_dword v172, v[132:133], off
	global_load_dword v173, v[130:131], off
	s_add_i32 s70, s43, 12
	s_add_i32 s71, s52, 12
	v_or_b32_e32 v130, s70, v21
	v_or_b32_e32 v132, s71, v70
	v_lshlrev_b32_sdwa v134, v108, v132 dst_sel:DWORD dst_unused:UNUSED_PAD src0_sel:DWORD src1_sel:WORD_0
	v_lshlrev_b32_sdwa v135, v108, v130 dst_sel:DWORD dst_unused:UNUSED_PAD src0_sel:DWORD src1_sel:WORD_0
	v_mov_b32_e32 v131, v3
	v_mov_b32_e32 v133, v3
	global_load_dword v174, v134, s[14:15]
	global_load_dword v175, v135, s[14:15]
	v_lshlrev_b64 v[132:133], 14, v[132:133]
	v_lshlrev_b64 v[130:131], 14, v[130:131]
	v_lshl_add_u64 v[132:133], v[68:69], 0, v[132:133]
	v_lshl_add_u64 v[130:131], v[68:69], 0, v[130:131]
	global_load_dword v176, v[132:133], off
	global_load_dword v177, v[130:131], off
	s_add_i32 s70, s43, 16
	s_add_i32 s71, s52, 16
	v_or_b32_e32 v130, s70, v21
	v_or_b32_e32 v132, s71, v70
	v_lshlrev_b32_sdwa v134, v108, v132 dst_sel:DWORD dst_unused:UNUSED_PAD src0_sel:DWORD src1_sel:WORD_0
	v_lshlrev_b32_sdwa v135, v108, v130 dst_sel:DWORD dst_unused:UNUSED_PAD src0_sel:DWORD src1_sel:WORD_0
	v_mov_b32_e32 v131, v3
	v_mov_b32_e32 v133, v3
	global_load_dword v178, v134, s[14:15]
	global_load_dword v179, v135, s[14:15]
	v_lshlrev_b64 v[132:133], 14, v[132:133]
	v_lshlrev_b64 v[130:131], 14, v[130:131]
	v_lshl_add_u64 v[132:133], v[68:69], 0, v[132:133]
	v_lshl_add_u64 v[130:131], v[68:69], 0, v[130:131]
	global_load_dword v180, v[132:133], off
	global_load_dword v181, v[130:131], off
	s_add_i32 s70, s43, 20
	s_add_i32 s71, s52, 20
	v_or_b32_e32 v130, s70, v21
	v_or_b32_e32 v132, s71, v70
	v_lshlrev_b32_sdwa v134, v108, v132 dst_sel:DWORD dst_unused:UNUSED_PAD src0_sel:DWORD src1_sel:WORD_0
	v_lshlrev_b32_sdwa v135, v108, v130 dst_sel:DWORD dst_unused:UNUSED_PAD src0_sel:DWORD src1_sel:WORD_0
	v_mov_b32_e32 v131, v3
	v_mov_b32_e32 v133, v3
	global_load_dword v182, v134, s[14:15]
	global_load_dword v183, v135, s[14:15]
	v_lshlrev_b64 v[132:133], 14, v[132:133]
	v_lshlrev_b64 v[130:131], 14, v[130:131]
	v_lshl_add_u64 v[132:133], v[68:69], 0, v[132:133]
	v_lshl_add_u64 v[130:131], v[68:69], 0, v[130:131]
	global_load_dword v184, v[132:133], off
	global_load_dword v185, v[130:131], off
	s_add_i32 s70, s43, 24
	s_add_i32 s71, s52, 24
	v_or_b32_e32 v130, s70, v21
	v_or_b32_e32 v132, s71, v70
	v_lshlrev_b32_sdwa v134, v108, v132 dst_sel:DWORD dst_unused:UNUSED_PAD src0_sel:DWORD src1_sel:WORD_0
	v_lshlrev_b32_sdwa v135, v108, v130 dst_sel:DWORD dst_unused:UNUSED_PAD src0_sel:DWORD src1_sel:WORD_0
	v_mov_b32_e32 v131, v3
	v_mov_b32_e32 v133, v3
	global_load_dword v186, v134, s[14:15]
	global_load_dword v187, v135, s[14:15]
	v_lshlrev_b64 v[132:133], 14, v[132:133]
	v_lshlrev_b64 v[130:131], 14, v[130:131]
	v_lshl_add_u64 v[132:133], v[68:69], 0, v[132:133]
	v_lshl_add_u64 v[130:131], v[68:69], 0, v[130:131]
	global_load_dword v188, v[132:133], off
	global_load_dword v189, v[130:131], off
	s_add_i32 s70, s43, 28
	s_add_i32 s71, s52, 28
	v_or_b32_e32 v130, s70, v21
	v_or_b32_e32 v132, s71, v70
	v_lshlrev_b32_sdwa v134, v108, v132 dst_sel:DWORD dst_unused:UNUSED_PAD src0_sel:DWORD src1_sel:WORD_0
	v_lshlrev_b32_sdwa v135, v108, v130 dst_sel:DWORD dst_unused:UNUSED_PAD src0_sel:DWORD src1_sel:WORD_0
	v_mov_b32_e32 v131, v3
	v_mov_b32_e32 v133, v3
	global_load_dword v190, v134, s[14:15]
	global_load_dword v191, v135, s[14:15]
	v_lshlrev_b64 v[132:133], 14, v[132:133]
	v_lshlrev_b64 v[130:131], 14, v[130:131]
	v_lshl_add_u64 v[132:133], v[68:69], 0, v[132:133]
	v_lshl_add_u64 v[130:131], v[68:69], 0, v[130:131]
	global_load_dword v192, v[132:133], off
	global_load_dword v193, v[130:131], off
	s_add_i32 s29, s29, 16
	s_add_i32 s28, s28, 16
	s_add_i32 s33, s33, -16
	s_waitcnt vmcnt(0)
	v_or_b32_e32 v61, s43, v1
	v_or_b32_e32 v71, s52, v20
	v_pk_mul_f32 v[72:73], v[162:163], v[164:165]
	v_mad_u64_u32 v[74:75], vcc, v71, s56, v[22:23]
	v_mad_u64_u32 v[76:77], vcc, v61, s56, v[22:23]
	ds_write_b32 v74, v72
	ds_write_b32 v76, v73
	s_add_i32 s70, s43, 4
	s_add_i32 s71, s52, 4
	v_or_b32_e32 v61, s70, v1
	v_or_b32_e32 v71, s71, v20
	v_pk_mul_f32 v[72:73], v[166:167], v[168:169]
	v_mad_u64_u32 v[74:75], vcc, v71, s56, v[22:23]
	v_mad_u64_u32 v[76:77], vcc, v61, s56, v[22:23]
	ds_write_b32 v74, v72
	ds_write_b32 v76, v73
	s_add_i32 s70, s43, 8
	s_add_i32 s71, s52, 8
	v_or_b32_e32 v61, s70, v1
	v_or_b32_e32 v71, s71, v20
	v_pk_mul_f32 v[72:73], v[170:171], v[172:173]
	v_mad_u64_u32 v[74:75], vcc, v71, s56, v[22:23]
	v_mad_u64_u32 v[76:77], vcc, v61, s56, v[22:23]
	ds_write_b32 v74, v72
	ds_write_b32 v76, v73
	s_add_i32 s70, s43, 12
	s_add_i32 s71, s52, 12
	v_or_b32_e32 v61, s70, v1
	v_or_b32_e32 v71, s71, v20
	v_pk_mul_f32 v[72:73], v[174:175], v[176:177]
	v_mad_u64_u32 v[74:75], vcc, v71, s56, v[22:23]
	v_mad_u64_u32 v[76:77], vcc, v61, s56, v[22:23]
	ds_write_b32 v74, v72
	ds_write_b32 v76, v73
	s_add_i32 s70, s43, 16
	s_add_i32 s71, s52, 16
	v_or_b32_e32 v61, s70, v1
	v_or_b32_e32 v71, s71, v20
	v_pk_mul_f32 v[72:73], v[178:179], v[180:181]
	v_mad_u64_u32 v[74:75], vcc, v71, s56, v[22:23]
	v_mad_u64_u32 v[76:77], vcc, v61, s56, v[22:23]
	ds_write_b32 v74, v72
	ds_write_b32 v76, v73
	s_add_i32 s70, s43, 20
	s_add_i32 s71, s52, 20
	v_or_b32_e32 v61, s70, v1
	v_or_b32_e32 v71, s71, v20
	v_pk_mul_f32 v[72:73], v[182:183], v[184:185]
	v_mad_u64_u32 v[74:75], vcc, v71, s56, v[22:23]
	v_mad_u64_u32 v[76:77], vcc, v61, s56, v[22:23]
	ds_write_b32 v74, v72
	ds_write_b32 v76, v73
	s_add_i32 s70, s43, 24
	s_add_i32 s71, s52, 24
	v_or_b32_e32 v61, s70, v1
	v_or_b32_e32 v71, s71, v20
	v_pk_mul_f32 v[72:73], v[186:187], v[188:189]
	v_mad_u64_u32 v[74:75], vcc, v71, s56, v[22:23]
	v_mad_u64_u32 v[76:77], vcc, v61, s56, v[22:23]
	ds_write_b32 v74, v72
	ds_write_b32 v76, v73
	s_add_i32 s70, s43, 28
	s_add_i32 s71, s52, 28
	v_or_b32_e32 v61, s70, v1
	v_or_b32_e32 v71, s71, v20
	v_pk_mul_f32 v[72:73], v[190:191], v[192:193]
	v_mad_u64_u32 v[74:75], vcc, v71, s56, v[22:23]
	v_mad_u64_u32 v[76:77], vcc, v61, s56, v[22:23]
	ds_write_b32 v74, v72
	ds_write_b32 v76, v73
	s_add_i32 s43, s43, 28
	s_add_i32 s52, s52, 28
	s_cmp_lg_u32 s33, 0
	s_cbranch_scc1 .LBB0_80
	s_waitcnt lgkmcnt(0)
	ds_read2_b32 v[72:73], v99 offset1:8
	ds_read2_b32 v[76:77], v99 offset0:33 offset1:41
	ds_read2_b32 v[78:79], v99 offset0:66 offset1:74
	ds_read2_b32 v[80:81], v99 offset0:99 offset1:107
	ds_read2_b32 v[82:83], v99 offset0:132 offset1:140
	ds_read2_b32 v[84:85], v99 offset0:165 offset1:173
	s_waitcnt lgkmcnt(5)
	v_bfe_u32 v2, v72, 16, 1
	v_add3_u32 v2, v72, v2, s62
	s_waitcnt lgkmcnt(4)
	v_bfe_u32 v21, v76, 16, 1
	v_lshrrev_b32_e32 v2, 16, v2
	v_add3_u32 v21, v76, v21, s62
	v_and_or_b32 v68, v21, s63, v2
	s_waitcnt lgkmcnt(3)
	v_bfe_u32 v2, v78, 16, 1
	v_add3_u32 v2, v78, v2, s62
	s_waitcnt lgkmcnt(2)
	v_bfe_u32 v21, v80, 16, 1
	ds_read2_b32 v[86:87], v99 offset0:198 offset1:206
	v_lshrrev_b32_e32 v2, 16, v2
	v_add3_u32 v21, v80, v21, s62
	ds_read2_b32 v[88:89], v99 offset0:231 offset1:239
	v_and_or_b32 v69, v21, s63, v2
	s_waitcnt lgkmcnt(3)
	v_bfe_u32 v2, v82, 16, 1
	v_add3_u32 v2, v82, v2, s62
	s_waitcnt lgkmcnt(2)
	v_bfe_u32 v21, v84, 16, 1
	v_lshrrev_b32_e32 v2, 16, v2
	v_add3_u32 v21, v84, v21, s62
	v_and_or_b32 v70, v21, s63, v2
	s_waitcnt lgkmcnt(1)
	v_bfe_u32 v2, v86, 16, 1
	v_add3_u32 v2, v86, v2, s62
	s_waitcnt lgkmcnt(0)
	v_bfe_u32 v21, v88, 16, 1
	v_lshrrev_b32_e32 v2, 16, v2
	v_add3_u32 v21, v88, v21, s62
	s_lshl_b32 s52, s3, 1
	v_and_or_b32 v71, v21, s63, v2
	v_or_b32_e32 v2, s2, v23
	v_lshl_add_u64 v[74:75], v[12:13], 0, s[52:53]
	v_lshlrev_b32_e32 v2, 11, v2
	v_lshl_add_u64 v[90:91], v[74:75], 0, v[2:3]
	v_bfe_u32 v2, v73, 16, 1
	v_add3_u32 v2, v73, v2, s62
	v_bfe_u32 v21, v77, 16, 1
	v_lshrrev_b32_e32 v2, 16, v2
	v_add3_u32 v21, v77, v21, s62
	global_store_dwordx4 v[90:91], v[68:71], off
	ds_read2_b32 v[72:73], v99 offset0:16 offset1:24
	s_nop 0
	v_and_or_b32 v68, v21, s63, v2
	v_bfe_u32 v2, v79, 16, 1
	v_add3_u32 v2, v79, v2, s62
	v_bfe_u32 v21, v81, 16, 1
	v_lshrrev_b32_e32 v2, 16, v2
	v_add3_u32 v21, v81, v21, s62
	v_and_or_b32 v69, v21, s63, v2
	v_bfe_u32 v2, v83, 16, 1
	v_add3_u32 v2, v83, v2, s62
	v_bfe_u32 v21, v85, 16, 1
	v_lshrrev_b32_e32 v2, 16, v2
	v_add3_u32 v21, v85, v21, s62
	v_and_or_b32 v70, v21, s63, v2
	v_bfe_u32 v2, v87, 16, 1
	v_add3_u32 v2, v87, v2, s62
	v_bfe_u32 v21, v89, 16, 1
	v_lshrrev_b32_e32 v2, 16, v2
	v_add3_u32 v21, v89, v21, s62
	v_and_or_b32 v71, v21, s63, v2
	v_or_b32_e32 v2, s2, v51
	v_lshlrev_b32_e32 v2, 11, v2
	v_lshl_add_u64 v[76:77], v[74:75], 0, v[2:3]
	global_store_dwordx4 v[76:77], v[68:71], off
	ds_read2_b32 v[76:77], v99 offset0:49 offset1:57
	ds_read2_b32 v[78:79], v99 offset0:82 offset1:90
	ds_read2_b32 v[80:81], v99 offset0:115 offset1:123
	s_waitcnt lgkmcnt(3)
	v_bfe_u32 v2, v72, 16, 1
	v_add3_u32 v2, v72, v2, s62
	s_waitcnt lgkmcnt(2)
	v_bfe_u32 v21, v76, 16, 1
	ds_read2_b32 v[82:83], v99 offset0:148 offset1:156
	v_lshrrev_b32_e32 v2, 16, v2
	v_add3_u32 v21, v76, v21, s62
	ds_read2_b32 v[84:85], v99 offset0:181 offset1:189
	v_and_or_b32 v68, v21, s63, v2
	s_waitcnt lgkmcnt(3)
	v_bfe_u32 v2, v78, 16, 1
	v_add3_u32 v2, v78, v2, s62
	s_waitcnt lgkmcnt(2)
	v_bfe_u32 v21, v80, 16, 1
	ds_read2_b32 v[86:87], v99 offset0:214 offset1:222
	v_lshrrev_b32_e32 v2, 16, v2
	v_add3_u32 v21, v80, v21, s62
	ds_read2_b32 v[88:89], v99 offset0:247 offset1:255
	v_and_or_b32 v69, v21, s63, v2
	s_waitcnt lgkmcnt(3)
	v_bfe_u32 v2, v82, 16, 1
	v_add3_u32 v2, v82, v2, s62
	s_waitcnt lgkmcnt(2)
	v_bfe_u32 v21, v84, 16, 1
	v_lshrrev_b32_e32 v2, 16, v2
	v_add3_u32 v21, v84, v21, s62
	v_and_or_b32 v70, v21, s63, v2
	s_waitcnt lgkmcnt(1)
	v_bfe_u32 v2, v86, 16, 1
	v_add3_u32 v2, v86, v2, s62
	s_waitcnt lgkmcnt(0)
	v_bfe_u32 v21, v88, 16, 1
	v_lshrrev_b32_e32 v2, 16, v2
	v_add3_u32 v21, v88, v21, s62
	v_and_or_b32 v71, v21, s63, v2
	v_or_b32_e32 v2, s2, v53
	v_lshlrev_b32_e32 v2, 11, v2
	v_lshl_add_u64 v[90:91], v[74:75], 0, v[2:3]
	v_bfe_u32 v2, v73, 16, 1
	v_add3_u32 v2, v73, v2, s62
	v_bfe_u32 v21, v77, 16, 1
	v_lshrrev_b32_e32 v2, 16, v2
	v_add3_u32 v21, v77, v21, s62
	global_store_dwordx4 v[90:91], v[68:71], off
	s_nop 1
	v_and_or_b32 v68, v21, s63, v2
	v_bfe_u32 v2, v79, 16, 1
	v_add3_u32 v2, v79, v2, s62
	v_bfe_u32 v21, v81, 16, 1
	v_lshrrev_b32_e32 v2, 16, v2
	v_add3_u32 v21, v81, v21, s62
	v_and_or_b32 v69, v21, s63, v2
	v_bfe_u32 v2, v83, 16, 1
	v_add3_u32 v2, v83, v2, s62
	v_bfe_u32 v21, v85, 16, 1
	v_lshrrev_b32_e32 v2, 16, v2
	v_add3_u32 v21, v85, v21, s62
	v_and_or_b32 v70, v21, s63, v2
	v_bfe_u32 v2, v87, 16, 1
	v_add3_u32 v2, v87, v2, s62
	v_bfe_u32 v21, v89, 16, 1
	v_lshrrev_b32_e32 v2, 16, v2
	v_add3_u32 v21, v89, v21, s62
	v_and_or_b32 v71, v21, s63, v2
	v_or_b32_e32 v2, s2, v98
	v_lshlrev_b32_e32 v2, 11, v2
	v_lshl_add_u64 v[72:73], v[74:75], 0, v[2:3]
	global_store_dwordx4 v[72:73], v[68:71], off
	s_waitcnt lgkmcnt(0)
